# Proj0/Proj1 epilogues: sumsq of the 4 row groups of an iteration preloaded at the first site (offsets 64/128/192), later sites use v_mov and drop the vmcnt(0) that also drained the previous group's st
# baseline (speedup 1.0000x reference)
;     DI void operator()(const pg8::f32x4 (&acc)[2][2][4][2], const pg8::Unit& u, int wr, int wc, int fr, int fq) const {
;     ...
;             const int col0 = cb + wc * 32 + 8 * fq;
;             const int region = cb >> 9;
; #pragma unroll
;             for (int ai = 0; ai < 2; ++ai)
; #pragma unroll
;                 for (int m = 0; m < 4; ++m) {
;                     const int row = row0 + ai * 128 + m * 16;
;                     const float rstd = rsqrtf(sumsq[row] * (1.0f / 1024.0f) + EPS);
;                     const int s = row & (SEQ - 1), b = row >> 13;
;                     float v[8];
; #pragma unroll
;                     for (int n = 0; n < 2; ++n)
; #pragma unroll
;                         for (int e = 0; e < 4; ++e) v[4 * n + e] = acc[ai][bj][m][n][e] * rstd;
.LBB0_182:
	s_cmp_lg_u32 s50, 12
	s_cselect_b64 s[16:17], -1, 0
	s_cmp_eq_u32 s50, 12
	s_cselect_b64 s[0:1], -1, 0
	s_and_b64 s[6:7], s[36:37], s[0:1]
	s_movk_i32 s0, 0xc00
	s_and_b64 vcc, exec, s[6:7]
	s_cbranch_vccnz .LBB0_659
	v_ashrrev_i32_e32 v167, 31, v166
	v_lshl_add_u64 v[172:173], v[166:167], 2, s[28:29]
	global_load_dword v12, v[172:173], off
	global_load_dword v196, v[172:173], off offset:64
	global_load_dword v197, v[172:173], off offset:128
	global_load_dword v198, v[172:173], off offset:192
	s_ashr_i32 s39, s50, 1
	s_cmp_eq_u32 s39, 2
	v_or_b32_e32 v168, s48, v156
	v_ashrrev_i32_e32 v10, 4, v166
	s_cselect_b64 s[52:53], -1, 0
	s_lshl_b32 s0, s39, 9
	v_and_b32_e32 v10, 0xfffffe00, v10
	v_subrev_u32_e32 v185, s0, v168
	v_add_u32_e32 v10, v10, v185
	v_ashrrev_i32_e32 v11, 31, v10
	v_lshlrev_b64 v[174:175], 14, v[10:11]
	s_cmp_gt_i32 s39, 1
	s_cselect_b64 s[0:1], -1, 0
	s_xor_b64 s[6:7], s[34:35], -1
	s_or_b64 s[54:55], s[6:7], s[0:1]
	s_cmp_lt_u32 s50, 2
	s_cselect_b64 s[0:1], -1, 0
	s_cmp_eq_u32 s39, 3
	s_cselect_b64 s[8:9], -1, 0
	s_and_b64 s[6:7], exec, s[16:17]
	s_or_b64 s[8:9], s[0:1], s[8:9]
	s_mov_b64 s[10:11], -1
	v_ashrrev_i32_e32 v169, 31, v168
	v_cndmask_b32_e64 v170, 1.0, v182, s[8:9]
	s_waitcnt vmcnt(0)
	v_fmamk_f32 v10, v12, 0x3a800000, v181
	v_mul_f32_e32 v11, 0x4b800000, v10
	v_cmp_gt_f32_e32 vcc, s87, v10
	s_nop 1
	v_cndmask_b32_e32 v10, v10, v11, vcc
	v_rsq_f32_e32 v10, v10
	s_nop 0
	v_mul_f32_e32 v11, 0x45800000, v10
	v_cndmask_b32_e32 v10, v10, v11, vcc
	v_pk_mul_f32 v[2:3], v[2:3], v[10:11] op_sel_hi:[1,0]
	v_pk_mul_f32 v[4:5], v[4:5], v[10:11] op_sel_hi:[1,0]
	v_pk_mul_f32 v[6:7], v[6:7], v[10:11] op_sel_hi:[1,0]
	v_pk_mul_f32 v[8:9], v[8:9], v[10:11] op_sel_hi:[1,0]
	s_mov_b64 vcc, s[6:7]
	s_cbranch_vccz .LBB0_192
	s_cmp_lt_i32 s39, 5
	s_cbranch_scc1 .LBB0_186
	s_cmp_lg_u32 s39, 5
	s_mov_b64 s[6:7], -1
	s_cselect_b64 s[8:9], -1, 0
	s_cbranch_execz .LBB0_187
	s_branch .LBB0_188

;     DI void operator()(const pg8::f32x4 (&acc)[2][2][4][2], const pg8::Unit& u, int wr, int wc, int fr, int fq) const {
;     ...
;                     const int row = row0 + ai * 128 + m * 16;
;                     const float rstd = rsqrtf(sumsq[row] * (1.0f / 1024.0f) + EPS);
;                     const int s = row & (SEQ - 1), b = row >> 13;
;                     float v[8];
; #pragma unroll
;                     for (int n = 0; n < 2; ++n)
; #pragma unroll
;                         for (int e = 0; e < 4; ++e) v[4 * n + e] = acc[ai][bj][m][n][e] * rstd;
.LBB0_196:
	v_or_b32_e32 v138, 16, v166
	v_ashrrev_i32_e32 v139, 31, v138
	v_mov_b32_e32 v2, v196
	s_andn2_b64 vcc, exec, s[16:17]
	v_fmamk_f32 v2, v2, 0x3a800000, v181
	v_mul_f32_e32 v3, 0x4b800000, v2
	v_cmp_gt_f32_e64 s[8:9], s87, v2
	s_nop 1
	v_cndmask_b32_e64 v2, v2, v3, s[8:9]
	v_rsq_f32_e32 v2, v2
	v_cndmask_b32_e64 v3, 0, 1, s[16:17]
	v_cmp_ne_u32_e64 s[6:7], 1, v3
	v_mul_f32_e32 v3, 0x45800000, v2
	v_cndmask_b32_e64 v8, v2, v3, s[8:9]
	v_pk_mul_f32 v[2:3], v[134:135], v[8:9] op_sel_hi:[1,0]
	v_pk_mul_f32 v[4:5], v[136:137], v[8:9] op_sel_hi:[1,0]
	v_pk_mul_f32 v[6:7], v[130:131], v[8:9] op_sel_hi:[1,0]
	v_pk_mul_f32 v[8:9], v[132:133], v[8:9] op_sel_hi:[1,0]
	s_mov_b64 s[8:9], -1
	s_cbranch_vccnz .LBB0_258
	s_cmp_lt_i32 s39, 5
	s_cbranch_scc1 .LBB0_252
	s_cmp_lg_u32 s39, 5
	s_cselect_b64 s[10:11], -1, 0
	s_cbranch_execz .LBB0_253
	s_branch .LBB0_254

;     DI void operator()(const pg8::f32x4 (&acc)[2][2][4][2], const pg8::Unit& u, int wr, int wc, int fr, int fq) const {
;     ...
;                     const int row = row0 + ai * 128 + m * 16;
;                     const float rstd = rsqrtf(sumsq[row] * (1.0f / 1024.0f) + EPS);
;                     const int s = row & (SEQ - 1), b = row >> 13;
;                     float v[8];
; #pragma unroll
;                     for (int n = 0; n < 2; ++n)
; #pragma unroll
;                         for (int e = 0; e < 4; ++e) v[4 * n + e] = acc[ai][bj][m][n][e] * rstd;
.LBB0_262:
	v_or_b32_e32 v130, 32, v166
	v_ashrrev_i32_e32 v131, 31, v130
	v_mov_b32_e32 v2, v197
	s_and_b64 vcc, exec, s[6:7]
	v_fmamk_f32 v2, v2, 0x3a800000, v181
	v_mul_f32_e32 v3, 0x4b800000, v2
	v_cmp_gt_f32_e64 s[8:9], s87, v2
	s_nop 1
	v_cndmask_b32_e64 v2, v2, v3, s[8:9]
	v_rsq_f32_e32 v2, v2
	s_nop 0
	v_mul_f32_e32 v3, 0x45800000, v2
	v_cndmask_b32_e64 v8, v2, v3, s[8:9]
	v_pk_mul_f32 v[2:3], v[126:127], v[8:9] op_sel_hi:[1,0]
	v_pk_mul_f32 v[4:5], v[128:129], v[8:9] op_sel_hi:[1,0]
	v_pk_mul_f32 v[6:7], v[122:123], v[8:9] op_sel_hi:[1,0]
	v_pk_mul_f32 v[8:9], v[124:125], v[8:9] op_sel_hi:[1,0]
	s_mov_b64 s[8:9], -1
	s_cbranch_vccnz .LBB0_324
	s_cmp_lt_i32 s39, 5
	s_cbranch_scc1 .LBB0_318
	s_cmp_lg_u32 s39, 5
	s_cselect_b64 s[10:11], -1, 0
	s_cbranch_execz .LBB0_319
	s_branch .LBB0_320

;     DI void operator()(const pg8::f32x4 (&acc)[2][2][4][2], const pg8::Unit& u, int wr, int wc, int fr, int fq) const {
;     ...
;                     const int row = row0 + ai * 128 + m * 16;
;                     const float rstd = rsqrtf(sumsq[row] * (1.0f / 1024.0f) + EPS);
;                     const int s = row & (SEQ - 1), b = row >> 13;
;                     float v[8];
; #pragma unroll
;                     for (int n = 0; n < 2; ++n)
; #pragma unroll
;                         for (int e = 0; e < 4; ++e) v[4 * n + e] = acc[ai][bj][m][n][e] * rstd;
.LBB0_328:
	v_or_b32_e32 v122, 48, v166
	v_ashrrev_i32_e32 v123, 31, v122
	v_mov_b32_e32 v2, v198
	s_and_b64 vcc, exec, s[6:7]
	v_fmamk_f32 v2, v2, 0x3a800000, v181
	v_mul_f32_e32 v3, 0x4b800000, v2
	v_cmp_gt_f32_e64 s[8:9], s87, v2
	s_nop 1
	v_cndmask_b32_e64 v2, v2, v3, s[8:9]
	v_rsq_f32_e32 v2, v2
	s_nop 0
	v_mul_f32_e32 v3, 0x45800000, v2
	v_cndmask_b32_e64 v8, v2, v3, s[8:9]
	v_pk_mul_f32 v[2:3], v[118:119], v[8:9] op_sel_hi:[1,0]
	v_pk_mul_f32 v[4:5], v[120:121], v[8:9] op_sel_hi:[1,0]
	v_pk_mul_f32 v[6:7], v[114:115], v[8:9] op_sel_hi:[1,0]
	v_pk_mul_f32 v[8:9], v[116:117], v[8:9] op_sel_hi:[1,0]
	s_mov_b64 s[8:9], -1
	s_cbranch_vccnz .LBB0_390
	s_cmp_lt_i32 s39, 5
	s_cbranch_scc1 .LBB0_384
	s_cmp_lg_u32 s39, 5
	s_cselect_b64 s[10:11], -1, 0
	s_cbranch_execz .LBB0_385
	s_branch .LBB0_386

;     DI void operator()(const pg8::f32x4 (&acc)[2][2][4][2], const pg8::Unit& u, int wr, int wc, int fr, int fq) const {
;     ...
;                     const int row = row0 + ai * 128 + m * 16;
;                     const float rstd = rsqrtf(sumsq[row] * (1.0f / 1024.0f) + EPS);
;                     const int s = row & (SEQ - 1), b = row >> 13;
;                     float v[8];
; #pragma unroll
;                     for (int n = 0; n < 2; ++n)
; #pragma unroll
;                         for (int e = 0; e < 4; ++e) v[4 * n + e] = acc[ai][bj][m][n][e] * rstd;
.LBB0_660:
	v_ashrrev_i32_e32 v167, 31, v166
	v_lshl_add_u64 v[84:85], v[166:167], 2, s[28:29]
	global_load_dword v2, v[84:85], off
	global_load_dword v196, v[84:85], off offset:64
	global_load_dword v197, v[84:85], off offset:128
	global_load_dword v198, v[84:85], off offset:192
	s_ashr_i32 s39, s50, 1
	s_cmp_eq_u32 s39, 2
	s_cselect_b64 s[10:11], -1, 0
	s_cmp_gt_i32 s39, 1
	s_cselect_b64 s[12:13], -1, 0
	s_cmp_lt_u32 s50, 2
	s_cselect_b64 s[16:17], -1, 0
	s_cmp_eq_u32 s39, 3
	s_mov_b64 s[52:53], -1
	s_mov_b64 s[8:9], 0
	s_cselect_b64 s[50:51], -1, 0
	s_cmp_lt_i32 s39, 5
	s_mov_b64 s[14:15], 0
	s_waitcnt vmcnt(0)
	v_fmamk_f32 v2, v2, 0x3a800000, v181
	v_cmp_gt_f32_e64 s[6:7], s87, v2
	s_cbranch_scc1 .LBB0_662
	s_cmp_lg_u32 s39, 5
	s_mov_b64 s[52:53], 0
	s_mov_b64 s[8:9], -1
	s_cselect_b64 s[14:15], -1, 0

;     DI void operator()(const pg8::f32x4 (&acc)[2][2][4][2], const pg8::Unit& u, int wr, int wc, int fr, int fq) const {
;     ...
;                     const int row = row0 + ai * 128 + m * 16;
;                     const float rstd = rsqrtf(sumsq[row] * (1.0f / 1024.0f) + EPS);
;                     const int s = row & (SEQ - 1), b = row >> 13;
;                     float v[8];
; #pragma unroll
;                     for (int n = 0; n < 2; ++n)
; #pragma unroll
;                         for (int e = 0; e < 4; ++e) v[4 * n + e] = acc[ai][bj][m][n][e] * rstd;
.LBB0_720:
	v_or_b32_e32 v76, 16, v166
	v_ashrrev_i32_e32 v77, 31, v76
	v_mov_b32_e32 v2, v196
	s_cmp_lt_i32 s39, 5
	v_fmamk_f32 v2, v2, 0x3a800000, v181
	v_cmp_gt_f32_e64 s[8:9], s87, v2
	s_cbranch_scc1 .LBB0_722
	s_cmp_lg_u32 s39, 5
	s_mov_b64 s[12:13], -1
	s_cselect_b64 s[14:15], -1, 0
	s_cbranch_execz .LBB0_723
	s_branch .LBB0_724

;     DI void operator()(const pg8::f32x4 (&acc)[2][2][4][2], const pg8::Unit& u, int wr, int wc, int fr, int fq) const {
;     ...
;                     const int row = row0 + ai * 128 + m * 16;
;                     const float rstd = rsqrtf(sumsq[row] * (1.0f / 1024.0f) + EPS);
;                     const int s = row & (SEQ - 1), b = row >> 13;
;                     float v[8];
; #pragma unroll
;                     for (int n = 0; n < 2; ++n)
; #pragma unroll
;                         for (int e = 0; e < 4; ++e) v[4 * n + e] = acc[ai][bj][m][n][e] * rstd;
.LBB0_780:
	v_or_b32_e32 v66, 32, v166
	v_ashrrev_i32_e32 v67, 31, v66
	v_mov_b32_e32 v2, v197
	s_cmp_lt_i32 s39, 5
	v_fmamk_f32 v2, v2, 0x3a800000, v181
	v_cmp_gt_f32_e64 s[8:9], s87, v2
	s_cbranch_scc1 .LBB0_782
	s_cmp_lg_u32 s39, 5
	s_mov_b64 s[12:13], -1
	s_cselect_b64 s[14:15], -1, 0
	s_cbranch_execz .LBB0_783
	s_branch .LBB0_784

;     DI void operator()(const pg8::f32x4 (&acc)[2][2][4][2], const pg8::Unit& u, int wr, int wc, int fr, int fq) const {
;     ...
;                     const int row = row0 + ai * 128 + m * 16;
;                     const float rstd = rsqrtf(sumsq[row] * (1.0f / 1024.0f) + EPS);
;                     const int s = row & (SEQ - 1), b = row >> 13;
;                     float v[8];
; #pragma unroll
;                     for (int n = 0; n < 2; ++n)
; #pragma unroll
;                         for (int e = 0; e < 4; ++e) v[4 * n + e] = acc[ai][bj][m][n][e] * rstd;
.LBB0_840:
	v_or_b32_e32 v58, 48, v166
	v_ashrrev_i32_e32 v59, 31, v58
	v_mov_b32_e32 v2, v198
	s_cmp_lt_i32 s39, 5
	v_fmamk_f32 v2, v2, 0x3a800000, v181
	v_cmp_gt_f32_e64 s[8:9], s87, v2
	s_cbranch_scc1 .LBB0_842
	s_cmp_lg_u32 s39, 5
	s_mov_b64 s[12:13], -1
	s_cselect_b64 s[14:15], -1, 0
	s_cbranch_execz .LBB0_843
	s_branch .LBB0_844

;     DI void operator()(const pg8::f32x4 (&acc)[2][2][4][2], const pg8::Unit& u, int wr, int wc, int fr, int fq) const {
;     ...
;             const int cb = u.pn * 256 + bj * 128;
;             if (cb > 3584) continue;
;             if (cb == 3584 && wc == 3) continue;
;             const int col0 = cb + wc * 32 + 8 * fq;
; #pragma unroll
;             for (int ai = 0; ai < 2; ++ai)
; #pragma unroll
;                 for (int m = 0; m < 4; ++m) {
;                     const int row = row0 + ai * 128 + m * 16;
;                     const float rstd = rsqrtf(sumsq[row] * (1.0f / 1024.0f) + EPS);
;                     const int s = row & (SEQ - 1), b = row >> 13;
;                     float v[8];
; #pragma unroll
;                     for (int n = 0; n < 2; ++n)
; #pragma unroll
;                         for (int e = 0; e < 4; ++e) v[4 * n + e] = acc[ai][bj][m][n][e] * rstd;
.LBB0_1555:
	s_lshl_b32 s35, s6, 8
	s_add_i32 s35, s35, s59
	s_lshl_b32 s44, s10, 8
	s_and_b32 s0, s10, 0xfffffc
	s_cmp_lg_u32 s0, 8
	s_cselect_b64 s[46:47], -1, 0
	s_cmp_gt_i32 s10, 14
	v_or_b32_e32 v172, s35, v1
	s_cbranch_scc1 .LBB0_2078
	s_cmp_lg_u32 s10, 14
	s_cselect_b64 s[48:49], -1, 0
	s_cmp_eq_u32 s10, 14
	s_cselect_b64 s[0:1], -1, 0
	s_and_b64 s[0:1], s[28:29], s[0:1]
	s_and_b64 vcc, exec, s[0:1]
	s_cbranch_vccnz .LBB0_2078
	v_ashrrev_i32_e32 v173, 31, v172
	v_lshl_add_u64 v[178:179], v[172:173], 2, s[16:17]
	global_load_dword v10, v[178:179], off
	global_load_dword v196, v[178:179], off offset:64
	global_load_dword v197, v[178:179], off offset:128
	global_load_dword v198, v[178:179], off offset:192
	s_cmp_lt_i32 s10, 4
	v_or_b32_e32 v174, s44, v160
	s_cselect_b64 vcc, -1, 0
	s_ashr_i32 s0, s35, 3
	v_add_u32_e32 v189, 0xfffff800, v174
	s_and_b32 s0, s0, 0xfffffc00
	s_mov_b64 s[8:9], -1
	v_cndmask_b32_e32 v176, 1.0, v187, vcc
	v_ashrrev_i32_e32 v175, 31, v174
	s_and_b64 vcc, exec, s[48:49]
	s_waitcnt vmcnt(0)
	v_fmamk_f32 v10, v10, 0x3a800000, v186
	v_mul_f32_e32 v11, 0x4b800000, v10
	v_cmp_gt_f32_e64 s[6:7], s81, v10
	s_nop 1
	v_cndmask_b32_e64 v10, v10, v11, s[6:7]
	v_rsq_f32_e32 v12, v10
	v_add_u32_e32 v10, s0, v189
	v_ashrrev_i32_e32 v11, 31, v10
	v_lshlrev_b64 v[180:181], 14, v[10:11]
	v_mul_f32_e32 v10, 0x45800000, v12
	v_cndmask_b32_e64 v10, v12, v10, s[6:7]
	v_pk_mul_f32 v[2:3], v[2:3], v[10:11] op_sel_hi:[1,0]
	v_pk_mul_f32 v[4:5], v[4:5], v[10:11] op_sel_hi:[1,0]
	v_pk_mul_f32 v[6:7], v[6:7], v[10:11] op_sel_hi:[1,0]
	v_pk_mul_f32 v[8:9], v[8:9], v[10:11] op_sel_hi:[1,0]
	s_cbranch_vccz .LBB0_1615
	v_and_b32_e32 v158, 0x1fcf, v172
	s_mov_b64 s[6:7], -1
	s_and_b64 vcc, exec, s[46:47]
	s_cbranch_vccz .LBB0_1612
	s_andn2_b64 vcc, exec, s[24:25]
	s_cbranch_vccnz .LBB0_1561
	v_mov_b64_e32 v[16:17], v[8:9]
	s_mov_b64 s[6:7], 0
	v_mov_b64_e32 v[14:15], v[6:7]
	v_mov_b64_e32 v[12:13], v[4:5]
	v_mov_b64_e32 v[10:11], v[2:3]

;     DI void operator()(const pg8::f32x4 (&acc)[2][2][4][2], const pg8::Unit& u, int wr, int wc, int fr, int fq) const {
;     ...
;                     const int row = row0 + ai * 128 + m * 16;
;                     const float rstd = rsqrtf(sumsq[row] * (1.0f / 1024.0f) + EPS);
;                     const int s = row & (SEQ - 1), b = row >> 13;
;                     float v[8];
; #pragma unroll
;                     for (int n = 0; n < 2; ++n)
; #pragma unroll
;                         for (int e = 0; e < 4; ++e) v[4 * n + e] = acc[ai][bj][m][n][e] * rstd;
.LBB0_1622:
	v_or_b32_e32 v142, 16, v172
	v_ashrrev_i32_e32 v143, 31, v142
	v_mov_b32_e32 v2, v196
	s_andn2_b64 vcc, exec, s[48:49]
	v_fmamk_f32 v2, v2, 0x3a800000, v186
	v_mul_f32_e32 v3, 0x4b800000, v2
	v_cmp_gt_f32_e64 s[8:9], s81, v2
	s_nop 1
	v_cndmask_b32_e64 v2, v2, v3, s[8:9]
	v_rsq_f32_e32 v2, v2
	v_cndmask_b32_e64 v3, 0, 1, s[48:49]
	v_cmp_ne_u32_e64 s[6:7], 1, v3
	v_mul_f32_e32 v3, 0x45800000, v2
	v_cndmask_b32_e64 v8, v2, v3, s[8:9]
	v_pk_mul_f32 v[2:3], v[134:135], v[8:9] op_sel_hi:[1,0]
	v_pk_mul_f32 v[4:5], v[136:137], v[8:9] op_sel_hi:[1,0]
	v_pk_mul_f32 v[6:7], v[130:131], v[8:9] op_sel_hi:[1,0]
	v_pk_mul_f32 v[8:9], v[132:133], v[8:9] op_sel_hi:[1,0]
	s_mov_b64 s[8:9], -1
	s_cbranch_vccnz .LBB0_1680
	v_and_b32_e32 v144, 0x1fdf, v142
	s_andn2_b64 vcc, exec, s[46:47]
	s_cbranch_vccnz .LBB0_1677
	s_andn2_b64 vcc, exec, s[24:25]
	s_cbranch_vccnz .LBB0_1626
	v_mov_b64_e32 v[16:17], v[8:9]
	s_mov_b64 s[8:9], 0
	v_mov_b64_e32 v[14:15], v[6:7]
	v_mov_b64_e32 v[12:13], v[4:5]
	v_mov_b64_e32 v[10:11], v[2:3]

;     DI void operator()(const pg8::f32x4 (&acc)[2][2][4][2], const pg8::Unit& u, int wr, int wc, int fr, int fq) const {
;     ...
;                     const int row = row0 + ai * 128 + m * 16;
;                     const float rstd = rsqrtf(sumsq[row] * (1.0f / 1024.0f) + EPS);
;                     const int s = row & (SEQ - 1), b = row >> 13;
;                     float v[8];
; #pragma unroll
;                     for (int n = 0; n < 2; ++n)
; #pragma unroll
;                         for (int e = 0; e < 4; ++e) v[4 * n + e] = acc[ai][bj][m][n][e] * rstd;
.LBB0_1687:
	v_or_b32_e32 v134, 32, v172
	v_ashrrev_i32_e32 v135, 31, v134
	v_mov_b32_e32 v2, v197
	s_and_b64 vcc, exec, s[6:7]
	v_fmamk_f32 v2, v2, 0x3a800000, v186
	v_mul_f32_e32 v3, 0x4b800000, v2
	v_cmp_gt_f32_e64 s[8:9], s81, v2
	s_nop 1
	v_cndmask_b32_e64 v2, v2, v3, s[8:9]
	v_rsq_f32_e32 v2, v2
	s_nop 0
	v_mul_f32_e32 v3, 0x45800000, v2
	v_cndmask_b32_e64 v8, v2, v3, s[8:9]
	v_pk_mul_f32 v[2:3], v[126:127], v[8:9] op_sel_hi:[1,0]
	v_pk_mul_f32 v[4:5], v[128:129], v[8:9] op_sel_hi:[1,0]
	v_pk_mul_f32 v[6:7], v[122:123], v[8:9] op_sel_hi:[1,0]
	v_pk_mul_f32 v[8:9], v[124:125], v[8:9] op_sel_hi:[1,0]
	s_mov_b64 s[8:9], -1
	s_cbranch_vccnz .LBB0_1745
	v_and_b32_e32 v136, 0x1fef, v134
	s_andn2_b64 vcc, exec, s[46:47]
	s_cbranch_vccnz .LBB0_1742
	s_andn2_b64 vcc, exec, s[24:25]
	s_cbranch_vccnz .LBB0_1691
	v_mov_b64_e32 v[16:17], v[8:9]
	s_mov_b64 s[8:9], 0
	v_mov_b64_e32 v[14:15], v[6:7]
	v_mov_b64_e32 v[12:13], v[4:5]
	v_mov_b64_e32 v[10:11], v[2:3]

;     DI void operator()(const pg8::f32x4 (&acc)[2][2][4][2], const pg8::Unit& u, int wr, int wc, int fr, int fq) const {
;     ...
;                     const int row = row0 + ai * 128 + m * 16;
;                     const float rstd = rsqrtf(sumsq[row] * (1.0f / 1024.0f) + EPS);
;                     const int s = row & (SEQ - 1), b = row >> 13;
;                     float v[8];
; #pragma unroll
;                     for (int n = 0; n < 2; ++n)
; #pragma unroll
;                         for (int e = 0; e < 4; ++e) v[4 * n + e] = acc[ai][bj][m][n][e] * rstd;
.LBB0_1752:
	v_or_b32_e32 v126, 48, v172
	v_ashrrev_i32_e32 v127, 31, v126
	v_mov_b32_e32 v2, v198
	s_and_b64 vcc, exec, s[6:7]
	v_fmamk_f32 v2, v2, 0x3a800000, v186
	v_mul_f32_e32 v3, 0x4b800000, v2
	v_cmp_gt_f32_e64 s[8:9], s81, v2
	s_nop 1
	v_cndmask_b32_e64 v2, v2, v3, s[8:9]
	v_rsq_f32_e32 v2, v2
	s_nop 0
	v_mul_f32_e32 v3, 0x45800000, v2
	v_cndmask_b32_e64 v8, v2, v3, s[8:9]
	v_pk_mul_f32 v[2:3], v[118:119], v[8:9] op_sel_hi:[1,0]
	v_pk_mul_f32 v[4:5], v[120:121], v[8:9] op_sel_hi:[1,0]
	v_pk_mul_f32 v[6:7], v[114:115], v[8:9] op_sel_hi:[1,0]
	v_pk_mul_f32 v[8:9], v[116:117], v[8:9] op_sel_hi:[1,0]
	s_mov_b64 s[8:9], -1
	s_cbranch_vccnz .LBB0_1810
	v_and_b32_e32 v128, 0x1fff, v126
	s_andn2_b64 vcc, exec, s[46:47]
	s_cbranch_vccnz .LBB0_1807
	s_andn2_b64 vcc, exec, s[24:25]
	s_cbranch_vccnz .LBB0_1756
	v_mov_b64_e32 v[16:17], v[8:9]
	s_mov_b64 s[8:9], 0
	v_mov_b64_e32 v[14:15], v[6:7]
	v_mov_b64_e32 v[12:13], v[4:5]
	v_mov_b64_e32 v[10:11], v[2:3]

;     DI void operator()(const pg8::f32x4 (&acc)[2][2][4][2], const pg8::Unit& u, int wr, int wc, int fr, int fq) const {
;     ...
;                     const int row = row0 + ai * 128 + m * 16;
;                     const float rstd = rsqrtf(sumsq[row] * (1.0f / 1024.0f) + EPS);
;                     const int s = row & (SEQ - 1), b = row >> 13;
;                     float v[8];
; #pragma unroll
;                     for (int n = 0; n < 2; ++n)
; #pragma unroll
;                         for (int e = 0; e < 4; ++e) v[4 * n + e] = acc[ai][bj][m][n][e] * rstd;
.LBB0_2077:
.LBB0_2078:
	s_cmp_gt_i32 s10, 13
	s_cbranch_scc1 .LBB0_2528
	v_ashrrev_i32_e32 v173, 31, v172
	v_lshl_add_u64 v[84:85], v[172:173], 2, s[16:17]
	global_load_dword v2, v[84:85], off
	global_load_dword v196, v[84:85], off offset:64
	global_load_dword v197, v[84:85], off offset:128
	global_load_dword v198, v[84:85], off offset:192
	v_cndmask_b32_e64 v3, 0, 1, s[46:47]
	v_cmp_ne_u32_e64 s[6:7], 1, v3
	s_or_b32 s0, s44, 0x80
	s_cmpk_lt_i32 s0, 0x400
	v_cndmask_b32_e64 v10, 0, 1, s[24:25]
	s_cselect_b64 vcc, -1, 0
	v_and_b32_e32 v83, 0x1fcf, v172
	s_mov_b64 s[10:11], -1
	v_cndmask_b32_e32 v82, 1.0, v187, vcc
	s_andn2_b64 vcc, exec, s[46:47]
	s_waitcnt vmcnt(0)
	v_fmamk_f32 v2, v2, 0x3a800000, v186
	v_mul_f32_e32 v3, 0x4b800000, v2
	v_cmp_gt_f32_e64 s[8:9], s81, v2
	s_nop 1
	v_cndmask_b32_e64 v2, v2, v3, s[8:9]
	v_rsq_f32_e32 v2, v2
	s_nop 0
	v_mul_f32_e32 v3, 0x45800000, v2
	v_cndmask_b32_e64 v8, v2, v3, s[8:9]
	v_pk_mul_f32 v[2:3], v[78:79], v[8:9] op_sel_hi:[1,0]
	v_pk_mul_f32 v[4:5], v[80:81], v[8:9] op_sel_hi:[1,0]
	v_pk_mul_f32 v[6:7], v[74:75], v[8:9] op_sel_hi:[1,0]
	v_pk_mul_f32 v[8:9], v[76:77], v[8:9] op_sel_hi:[1,0]
	v_cmp_ne_u32_e64 s[8:9], 1, v10
	s_cbranch_vccnz .LBB0_2133
	s_and_b64 vcc, exec, s[8:9]
	s_cbranch_vccnz .LBB0_2082
	v_mov_b64_e32 v[16:17], v[8:9]
	s_mov_b64 s[10:11], 0
	v_mov_b64_e32 v[14:15], v[6:7]
	v_mov_b64_e32 v[12:13], v[4:5]
	v_mov_b64_e32 v[10:11], v[2:3]

;     DI void operator()(const pg8::f32x4 (&acc)[2][2][4][2], const pg8::Unit& u, int wr, int wc, int fr, int fq) const {
;     ...
;                     const int row = row0 + ai * 128 + m * 16;
;                     const float rstd = rsqrtf(sumsq[row] * (1.0f / 1024.0f) + EPS);
;                     const int s = row & (SEQ - 1), b = row >> 13;
;                     float v[8];
; #pragma unroll
;                     for (int n = 0; n < 2; ++n)
; #pragma unroll
;                         for (int e = 0; e < 4; ++e) v[4 * n + e] = acc[ai][bj][m][n][e] * rstd;
.LBB0_2135:
	v_or_b32_e32 v76, 16, v172
	v_ashrrev_i32_e32 v77, 31, v76
	v_mov_b32_e32 v2, v196
	v_bitop3_b32 v77, v172, s83, 16 bitop3:0xc8
	s_and_b64 vcc, exec, s[6:7]
	v_fmamk_f32 v2, v2, 0x3a800000, v186
	v_mul_f32_e32 v3, 0x4b800000, v2
	v_cmp_gt_f32_e64 s[10:11], s81, v2
	s_nop 1
	v_cndmask_b32_e64 v2, v2, v3, s[10:11]
	v_rsq_f32_e32 v2, v2
	s_nop 0
	v_mul_f32_e32 v3, 0x45800000, v2
	v_cndmask_b32_e64 v8, v2, v3, s[10:11]
	v_pk_mul_f32 v[2:3], v[70:71], v[8:9] op_sel_hi:[1,0]
	v_pk_mul_f32 v[4:5], v[72:73], v[8:9] op_sel_hi:[1,0]
	v_pk_mul_f32 v[6:7], v[66:67], v[8:9] op_sel_hi:[1,0]
	v_pk_mul_f32 v[8:9], v[68:69], v[8:9] op_sel_hi:[1,0]
	s_mov_b64 s[10:11], -1
	s_cbranch_vccnz .LBB0_2189
	s_and_b64 vcc, exec, s[8:9]
	s_cbranch_vccnz .LBB0_2138
	v_mov_b64_e32 v[16:17], v[8:9]
	s_mov_b64 s[10:11], 0
	v_mov_b64_e32 v[14:15], v[6:7]
	v_mov_b64_e32 v[12:13], v[4:5]
	v_mov_b64_e32 v[10:11], v[2:3]

;     DI void operator()(const pg8::f32x4 (&acc)[2][2][4][2], const pg8::Unit& u, int wr, int wc, int fr, int fq) const {
;     ...
;                     const int row = row0 + ai * 128 + m * 16;
;                     const float rstd = rsqrtf(sumsq[row] * (1.0f / 1024.0f) + EPS);
;                     const int s = row & (SEQ - 1), b = row >> 13;
;                     float v[8];
; #pragma unroll
;                     for (int n = 0; n < 2; ++n)
; #pragma unroll
;                         for (int e = 0; e < 4; ++e) v[4 * n + e] = acc[ai][bj][m][n][e] * rstd;
.LBB0_2191:
	v_or_b32_e32 v66, 32, v172
	v_ashrrev_i32_e32 v67, 31, v66
	v_mov_b32_e32 v2, v197
	v_bitop3_b32 v67, v172, s84, 32 bitop3:0xc8
	s_and_b64 vcc, exec, s[6:7]
	v_fmamk_f32 v2, v2, 0x3a800000, v186
	v_mul_f32_e32 v3, 0x4b800000, v2
	v_cmp_gt_f32_e64 s[10:11], s81, v2
	s_nop 1
	v_cndmask_b32_e64 v2, v2, v3, s[10:11]
	v_rsq_f32_e32 v2, v2
	s_nop 0
	v_mul_f32_e32 v3, 0x45800000, v2
	v_cndmask_b32_e64 v8, v2, v3, s[10:11]
	v_pk_mul_f32 v[2:3], v[62:63], v[8:9] op_sel_hi:[1,0]
	v_pk_mul_f32 v[4:5], v[64:65], v[8:9] op_sel_hi:[1,0]
	v_pk_mul_f32 v[6:7], v[58:59], v[8:9] op_sel_hi:[1,0]
	v_pk_mul_f32 v[8:9], v[60:61], v[8:9] op_sel_hi:[1,0]
	s_mov_b64 s[10:11], -1
	s_cbranch_vccnz .LBB0_2245
	s_and_b64 vcc, exec, s[8:9]
	s_cbranch_vccnz .LBB0_2194
	v_mov_b64_e32 v[16:17], v[8:9]
	s_mov_b64 s[10:11], 0
	v_mov_b64_e32 v[14:15], v[6:7]
	v_mov_b64_e32 v[12:13], v[4:5]
	v_mov_b64_e32 v[10:11], v[2:3]

;     DI void operator()(const pg8::f32x4 (&acc)[2][2][4][2], const pg8::Unit& u, int wr, int wc, int fr, int fq) const {
;     ...
;                     const int row = row0 + ai * 128 + m * 16;
;                     const float rstd = rsqrtf(sumsq[row] * (1.0f / 1024.0f) + EPS);
;                     const int s = row & (SEQ - 1), b = row >> 13;
;                     float v[8];
; #pragma unroll
;                     for (int n = 0; n < 2; ++n)
; #pragma unroll
;                         for (int e = 0; e < 4; ++e) v[4 * n + e] = acc[ai][bj][m][n][e] * rstd;
.LBB0_2247:
	v_or_b32_e32 v58, 48, v172
	v_ashrrev_i32_e32 v59, 31, v58
	v_mov_b32_e32 v2, v198
	v_bitop3_b32 v59, v172, s85, 48 bitop3:0xc8
	s_and_b64 vcc, exec, s[6:7]
	v_fmamk_f32 v2, v2, 0x3a800000, v186
	v_mul_f32_e32 v3, 0x4b800000, v2
	v_cmp_gt_f32_e64 s[10:11], s81, v2
	s_nop 1
	v_cndmask_b32_e64 v2, v2, v3, s[10:11]
	v_rsq_f32_e32 v2, v2
	s_nop 0
	v_mul_f32_e32 v3, 0x45800000, v2
	v_cndmask_b32_e64 v8, v2, v3, s[10:11]
	v_pk_mul_f32 v[2:3], v[54:55], v[8:9] op_sel_hi:[1,0]
	v_pk_mul_f32 v[4:5], v[56:57], v[8:9] op_sel_hi:[1,0]
	v_pk_mul_f32 v[6:7], v[50:51], v[8:9] op_sel_hi:[1,0]
	v_pk_mul_f32 v[8:9], v[52:53], v[8:9] op_sel_hi:[1,0]
	s_mov_b64 s[10:11], -1
	s_cbranch_vccnz .LBB0_2301
	s_and_b64 vcc, exec, s[8:9]
	s_cbranch_vccnz .LBB0_2250
	v_mov_b64_e32 v[16:17], v[8:9]
	s_mov_b64 s[10:11], 0
	v_mov_b64_e32 v[14:15], v[6:7]
	v_mov_b64_e32 v[12:13], v[4:5]
	v_mov_b64_e32 v[10:11], v[2:3]
